# v33 + moba_own top-3 arg-max butterfly: 40 of 48 ds_bpermute shuffle steps replaced by DPP row rotations (same reduction result)
# speedup vs baseline: 1.0101x; 1.0101x over previous
.LBB0_1135:
	s_or_b64 exec, exec, s[0:1]
	v_mov_b32_e32 v25, v24
	v_pk_mul_f32 v[8:9], v[24:25], v[8:9]
	v_pk_mul_f32 v[10:11], v[24:25], v[10:11]
	v_readlane_b32 s0, v237, 40
	v_cvt_pk_bf16_f32 v8, v8, v9
	v_cvt_pk_bf16_f32 v9, v10, v11
	v_lshlrev_b64 v[10:11], 12, v[14:15]
	v_readlane_b32 s1, v237, 41
	s_lshl_b32 s22, s7, 9
	v_lshlrev_b32_e32 v18, 1, v18
	v_lshl_add_u64 v[10:11], s[0:1], 0, v[10:11]
	v_lshl_add_u64 v[10:11], v[10:11], 0, s[22:23]
	v_pk_mul_f32 v[0:1], v[24:25], v[0:1]
	v_pk_mul_f32 v[2:3], v[24:25], v[2:3]
	v_lshl_add_u64 v[10:11], v[10:11], 0, v[18:19]
	v_cvt_pk_bf16_f32 v0, v0, v1
	v_cvt_pk_bf16_f32 v1, v2, v3
	global_store_dwordx2 v[10:11], v[0:1], off offset:64
	v_pk_mul_f32 v[0:1], v[24:25], v[4:5]
	v_pk_mul_f32 v[2:3], v[24:25], v[6:7]
	v_cvt_pk_bf16_f32 v0, v0, v1
	v_cvt_pk_bf16_f32 v1, v2, v3
	v_cmp_gt_i32_e32 vcc, 64, v20
	v_lshl_add_u32 v26, v20, 2, v37
	global_store_dwordx2 v[10:11], v[8:9], off offset:32
	global_store_dwordx2 v[10:11], v[0:1], off offset:96
	s_and_saveexec_b64 s[0:1], vcc
	ds_write_b32 v26, v19
	s_or_b64 exec, exec, s[0:1]
	v_bfe_u32 v23, v20, 4, 2
	v_lshlrev_b32_e32 v18, 4, v23
	s_ashr_i32 s25, s24, 31
	v_lshl_add_u64 v[24:25], v[12:13], 0, v[18:19]
	s_lshl_b64 s[0:1], s[24:25], 13
	s_waitcnt lgkmcnt(0)
	s_barrier
	global_load_dwordx4 v[0:3], v[24:25], off offset:1536
	global_load_dwordx4 v[42:45], v[24:25], off offset:1600
	s_add_u32 s0, s16, s0
	v_or_b32_e32 v27, 16, v21
	s_addc_u32 s1, s17, s1
	v_lshlrev_b32_e32 v4, 7, v21
	v_mov_b32_e32 v5, v19
	v_lshlrev_b32_e32 v8, 7, v27
	v_mov_b32_e32 v9, v19
	v_lshl_add_u64 v[4:5], s[0:1], 0, v[4:5]
	v_lshl_add_u64 v[8:9], s[0:1], 0, v[8:9]
	v_or_b32_e32 v28, 32, v21
	v_lshl_add_u64 v[50:51], v[4:5], 0, v[18:19]
	v_lshl_add_u64 v[54:55], v[8:9], 0, v[18:19]
	v_lshlrev_b32_e32 v12, 7, v28
	v_mov_b32_e32 v13, v19
	global_load_dwordx4 v[4:7], v[50:51], off
	global_load_dwordx4 v[8:11], v[54:55], off
	v_lshl_add_u64 v[12:13], s[0:1], 0, v[12:13]
	v_or_b32_e32 v29, 48, v21
	v_lshl_add_u64 v[58:59], v[12:13], 0, v[18:19]
	v_mov_b32_e32 v47, v19
	v_lshlrev_b32_e32 v46, 7, v29
	global_load_dwordx4 v[12:15], v[58:59], off
	v_lshl_add_u64 v[24:25], s[0:1], 0, v[46:47]
	v_lshl_add_u64 v[24:25], v[24:25], 0, v[18:19]
	global_load_dwordx4 v[46:49], v[24:25], off
	s_nop 0
	global_load_dwordx4 v[50:53], v[50:51], off offset:64
	v_xor_b32_e32 v18, 8, v31
	global_load_dwordx4 v[54:57], v[54:55], off offset:64
	v_cmp_lt_i32_e64 s[0:1], v18, v33
	global_load_dwordx4 v[58:61], v[58:59], off offset:64
	v_cmp_gt_u32_e64 s[8:9], s6, v21
	global_load_dwordx4 v[62:65], v[24:25], off offset:64
	v_cmp_gt_u32_e64 s[10:11], s6, v27
	v_cmp_gt_u32_e64 s[12:13], s6, v28
	v_cmp_gt_u32_e64 s[14:15], s6, v29
	s_waitcnt vmcnt(7)
	v_mfma_f32_16x16x32_bf16 v[4:7], v[0:3], v[4:7], 0
	s_waitcnt vmcnt(6)
	v_mfma_f32_16x16x32_bf16 v[8:11], v[0:3], v[8:11], 0
	s_waitcnt vmcnt(5)
	v_mfma_f32_16x16x32_bf16 v[12:15], v[0:3], v[12:15], 0
	s_waitcnt vmcnt(4)
	v_mfma_f32_16x16x32_bf16 v[46:49], v[0:3], v[46:49], 0
	s_waitcnt vmcnt(3)
	v_mfma_f32_16x16x32_bf16 v[0:3], v[42:45], v[50:53], v[4:7]
	s_waitcnt vmcnt(2)
	v_mfma_f32_16x16x32_bf16 v[4:7], v[42:45], v[54:57], v[8:11]
	s_waitcnt vmcnt(1)
	v_mfma_f32_16x16x32_bf16 v[8:11], v[42:45], v[58:61], v[12:15]
	s_nop 3
	v_cndmask_b32_e64 v0, v38, v0, s[8:9]
	v_cndmask_b32_e64 v12, v31, v18, s[0:1]
	v_lshlrev_b32_e32 v18, 2, v12
	s_waitcnt vmcnt(0)
	v_mfma_f32_16x16x32_bf16 v[12:15], v[42:45], v[62:65], v[46:49]
	v_cndmask_b32_e64 v42, v38, v4, s[10:11]
	v_cmp_gt_f32_e64 s[0:1], v42, v0
	v_cndmask_b32_e64 v43, v38, v8, s[12:13]
	s_nop 0
	v_cndmask_b32_e64 v8, v0, v42, s[0:1]
	v_cndmask_b32_e64 v4, v21, v27, s[0:1]
	v_cmp_gt_f32_e64 s[0:1], v43, v8
	s_nop 0
	v_cndmask_b32_e64 v44, v38, v12, s[14:15]
	v_cndmask_b32_e64 v8, v8, v43, s[0:1]
	v_cndmask_b32_e64 v4, v4, v28, s[0:1]
	v_cmp_gt_f32_e64 s[0:1], v44, v8
	s_nop 1
	v_cndmask_b32_e64 v46, v8, v44, s[0:1]
	v_cndmask_b32_e64 v45, v4, v29, s[0:1]
	s_nop 4
	v_mov_b32_dpp v4, v46 row_ror:8 row_mask:0xf bank_mask:0xf
	v_mov_b32_dpp v8, v45 row_ror:8 row_mask:0xf bank_mask:0xf
	v_cmp_gt_f32_e64 s[18:19], v4, v46
	v_cmp_eq_f32_e64 s[0:1], v4, v46
	v_cmp_lt_i32_e64 s[6:7], v8, v45
	s_and_b64 s[0:1], s[0:1], s[6:7]
	s_or_b64 s[18:19], s[18:19], s[0:1]
	v_cndmask_b32_e64 v46, v46, v4, s[18:19]
	v_cndmask_b32_e64 v45, v45, v8, s[18:19]
	v_xor_b32_e32 v4, 4, v31
	v_cmp_lt_i32_e64 s[0:1], v4, v33
	s_nop 1
	v_cndmask_b32_e64 v4, v31, v4, s[0:1]
	v_lshlrev_b32_e32 v4, 2, v4
	s_waitcnt lgkmcnt(0)
	s_nop 4
	v_mov_b32_dpp v8, v46 row_ror:4 row_mask:0xf bank_mask:0xf
	v_mov_b32_dpp v12, v45 row_ror:4 row_mask:0xf bank_mask:0xf
	v_cmp_gt_f32_e64 s[18:19], v8, v46
	v_cmp_eq_f32_e64 s[0:1], v8, v46
	v_cmp_lt_i32_e64 s[6:7], v12, v45
	s_and_b64 s[0:1], s[0:1], s[6:7]
	s_or_b64 s[18:19], s[18:19], s[0:1]
	v_cndmask_b32_e64 v46, v46, v8, s[18:19]
	v_cndmask_b32_e64 v45, v45, v12, s[18:19]
	v_xor_b32_e32 v8, 2, v31
	v_cmp_lt_i32_e64 s[0:1], v8, v33
	s_nop 1
	v_cndmask_b32_e64 v8, v31, v8, s[0:1]
	v_lshlrev_b32_e32 v8, 2, v8
	s_waitcnt lgkmcnt(0)
	s_nop 4
	v_mov_b32_dpp v12, v46 row_ror:2 row_mask:0xf bank_mask:0xf
	v_mov_b32_dpp v24, v45 row_ror:2 row_mask:0xf bank_mask:0xf
	v_cmp_gt_f32_e64 s[18:19], v12, v46
	v_cmp_eq_f32_e64 s[0:1], v12, v46
	v_cmp_lt_i32_e64 s[6:7], v24, v45
	s_and_b64 s[0:1], s[0:1], s[6:7]
	s_or_b64 s[18:19], s[18:19], s[0:1]
	v_cndmask_b32_e64 v46, v46, v12, s[18:19]
	v_cndmask_b32_e64 v45, v45, v24, s[18:19]
	v_xor_b32_e32 v12, 1, v31
	v_cmp_lt_i32_e64 s[0:1], v12, v33
	s_nop 1
	v_cndmask_b32_e64 v12, v31, v12, s[0:1]
	v_lshlrev_b32_e32 v12, 2, v12
	s_waitcnt lgkmcnt(0)
	s_nop 4
	v_mov_b32_dpp v24, v46 row_ror:1 row_mask:0xf bank_mask:0xf
	v_mov_b32_dpp v25, v45 row_ror:1 row_mask:0xf bank_mask:0xf
	v_cmp_gt_f32_e64 s[18:19], v24, v46
	v_cmp_eq_f32_e64 s[0:1], v24, v46
	v_cmp_lt_i32_e64 s[6:7], v25, v45
	s_and_b64 s[0:1], s[0:1], s[6:7]
	s_or_b64 s[18:19], s[18:19], s[0:1]
	v_cndmask_b32_e64 v46, v46, v24, s[18:19]
	v_cndmask_b32_e64 v45, v45, v25, s[18:19]
	v_lshl_or_b32 v22, v23, 2, v22
	v_ashrrev_i32_e32 v23, 31, v22
	s_waitcnt lgkmcnt(0)
	v_lshl_add_u64 v[24:25], s[28:29], 0, v[22:23]
	v_lshlrev_b64 v[24:25], 5, v[24:25]
	v_cmp_eq_u32_e64 s[6:7], 0, v21
	v_or_b32_e32 v24, s27, v24
	v_mul_lo_u32 v23, v22, 12
	s_and_saveexec_b64 s[18:19], s[6:7]
	s_cbranch_execz .LBB0_1158
	v_cmp_nlt_f32_e64 s[0:1], s42, v46
	v_add_u32_e32 v46, 0x12e00, v23
	s_and_saveexec_b64 s[30:31], s[0:1]
	s_xor_b64 s[0:1], exec, s[30:31]
	s_cbranch_execz .LBB0_1156
	v_lshlrev_b64 v[48:49], 2, v[24:25]
	v_or_b32_e32 v48, 4, v48
	ds_write_b32 v46, v35
	v_lshl_add_u64 v[46:47], s[2:3], 0, v[48:49]
	global_store_dword v[46:47], v30, off
	v_lshl_add_u64 v[46:47], s[20:21], 0, v[48:49]
	global_store_dword v[46:47], v19, off

.LBB0_1158:
	s_or_b64 exec, exec, s[18:19]
	v_cmp_ne_u32_e64 s[0:1], v21, v45
	s_nop 1
	v_cndmask_b32_e64 v0, v38, v0, s[0:1]
	v_cmp_ne_u32_e64 s[0:1], v27, v45
	s_nop 1
	v_cndmask_b32_e64 v42, v38, v42, s[0:1]
	v_cmp_ne_u32_e64 s[0:1], v28, v45
	s_nop 1
	v_cndmask_b32_e64 v43, v38, v43, s[0:1]
	v_cmp_ne_u32_e64 s[0:1], v29, v45
	s_nop 1
	v_cndmask_b32_e64 v44, v38, v44, s[0:1]
	v_cmp_gt_f32_e64 s[0:1], v42, v0
	s_nop 1
	v_cndmask_b32_e64 v46, v0, v42, s[0:1]
	v_cndmask_b32_e64 v45, v21, v27, s[0:1]
	v_cmp_gt_f32_e64 s[0:1], v43, v46
	s_nop 1
	v_cndmask_b32_e64 v46, v46, v43, s[0:1]
	v_cndmask_b32_e64 v45, v45, v28, s[0:1]
	v_cmp_gt_f32_e64 s[0:1], v44, v46
	s_nop 1
	v_cndmask_b32_e64 v46, v46, v44, s[0:1]
	v_cndmask_b32_e64 v45, v45, v29, s[0:1]
	s_nop 4
	v_mov_b32_dpp v47, v46 row_ror:8 row_mask:0xf bank_mask:0xf
	v_mov_b32_dpp v48, v45 row_ror:8 row_mask:0xf bank_mask:0xf
	v_cmp_gt_f32_e64 s[30:31], v47, v46
	v_cmp_eq_f32_e64 s[0:1], v47, v46
	v_cmp_lt_i32_e64 s[18:19], v48, v45
	s_and_b64 s[0:1], s[0:1], s[18:19]
	s_or_b64 s[30:31], s[30:31], s[0:1]
	v_cndmask_b32_e64 v46, v46, v47, s[30:31]
	v_cndmask_b32_e64 v45, v45, v48, s[30:31]
	s_nop 4
	v_mov_b32_dpp v47, v46 row_ror:4 row_mask:0xf bank_mask:0xf
	v_mov_b32_dpp v48, v45 row_ror:4 row_mask:0xf bank_mask:0xf
	v_cmp_gt_f32_e64 s[30:31], v47, v46
	v_cmp_eq_f32_e64 s[0:1], v47, v46
	v_cmp_lt_i32_e64 s[18:19], v48, v45
	s_and_b64 s[0:1], s[0:1], s[18:19]
	s_or_b64 s[30:31], s[30:31], s[0:1]
	v_cndmask_b32_e64 v46, v46, v47, s[30:31]
	v_cndmask_b32_e64 v45, v45, v48, s[30:31]
	s_nop 4
	v_mov_b32_dpp v47, v46 row_ror:2 row_mask:0xf bank_mask:0xf
	v_mov_b32_dpp v48, v45 row_ror:2 row_mask:0xf bank_mask:0xf
	v_cmp_gt_f32_e64 s[30:31], v47, v46
	v_cmp_eq_f32_e64 s[0:1], v47, v46
	v_cmp_lt_i32_e64 s[18:19], v48, v45
	s_and_b64 s[0:1], s[0:1], s[18:19]
	s_or_b64 s[30:31], s[30:31], s[0:1]
	v_cndmask_b32_e64 v46, v46, v47, s[30:31]
	v_cndmask_b32_e64 v45, v45, v48, s[30:31]
	ds_bpermute_b32 v47, v12, v46
	s_waitcnt lgkmcnt(1)
	ds_bpermute_b32 v48, v12, v45
	s_waitcnt lgkmcnt(1)
	v_cmp_lt_f32_e64 s[30:31], v46, v47
	v_cmp_nlt_f32_e64 s[0:1], v46, v47
	s_and_saveexec_b64 s[34:35], s[0:1]
	s_cbranch_execz .LBB0_1173
	v_cmp_eq_f32_e64 s[0:1], v46, v47
	s_waitcnt lgkmcnt(0)
	v_cmp_lt_i32_e64 s[18:19], v48, v45
	s_and_b64 s[0:1], s[0:1], s[18:19]
	s_andn2_b64 s[18:19], s[30:31], exec
	s_and_b64 s[0:1], s[0:1], exec
	s_or_b64 s[30:31], s[18:19], s[0:1]
	s_or_b64 exec, exec, s[34:35]
	s_and_saveexec_b64 s[0:1], s[30:31]
	s_cbranch_execnz .LBB0_1174

.LBB0_1179:
	s_or_b64 exec, exec, s[18:19]
	v_cmp_ne_u32_e64 s[0:1], v21, v45
	s_nop 1
	v_cndmask_b32_e64 v0, v38, v0, s[0:1]
	v_cmp_ne_u32_e64 s[0:1], v27, v45
	s_nop 1
	v_cndmask_b32_e64 v42, v38, v42, s[0:1]
	v_cmp_ne_u32_e64 s[0:1], v28, v45
	s_nop 1
	v_cndmask_b32_e64 v43, v38, v43, s[0:1]
	v_cmp_ne_u32_e64 s[0:1], v29, v45
	s_nop 1
	v_cndmask_b32_e64 v44, v38, v44, s[0:1]
	v_cmp_gt_f32_e64 s[0:1], v42, v0
	s_nop 1
	v_cndmask_b32_e64 v0, v0, v42, s[0:1]
	v_cndmask_b32_e64 v45, v21, v27, s[0:1]
	v_cmp_gt_f32_e64 s[0:1], v43, v0
	s_nop 1
	v_cndmask_b32_e64 v43, v0, v43, s[0:1]
	v_cndmask_b32_e64 v42, v45, v28, s[0:1]
	v_cmp_gt_f32_e64 s[0:1], v44, v43
	s_nop 1
	v_cndmask_b32_e64 v0, v42, v29, s[0:1]
	v_cndmask_b32_e64 v42, v43, v44, s[0:1]
	s_nop 4
	v_mov_b32_dpp v43, v42 row_ror:8 row_mask:0xf bank_mask:0xf
	v_mov_b32_dpp v44, v0 row_ror:8 row_mask:0xf bank_mask:0xf
	v_cmp_gt_f32_e64 s[30:31], v43, v42
	v_cmp_eq_f32_e64 s[0:1], v43, v42
	v_cmp_lt_i32_e64 s[18:19], v44, v0
	s_and_b64 s[0:1], s[0:1], s[18:19]
	s_or_b64 s[30:31], s[30:31], s[0:1]
	v_cndmask_b32_e64 v42, v42, v43, s[30:31]
	v_cndmask_b32_e64 v0, v0, v44, s[30:31]
	s_nop 4
	v_mov_b32_dpp v43, v42 row_ror:4 row_mask:0xf bank_mask:0xf
	v_mov_b32_dpp v44, v0 row_ror:4 row_mask:0xf bank_mask:0xf
	v_cmp_gt_f32_e64 s[30:31], v43, v42
	v_cmp_eq_f32_e64 s[0:1], v43, v42
	v_cmp_lt_i32_e64 s[18:19], v44, v0
	s_and_b64 s[0:1], s[0:1], s[18:19]
	s_or_b64 s[30:31], s[30:31], s[0:1]
	v_cndmask_b32_e64 v42, v42, v43, s[30:31]
	v_cndmask_b32_e64 v0, v0, v44, s[30:31]
	s_nop 4
	v_mov_b32_dpp v43, v42 row_ror:2 row_mask:0xf bank_mask:0xf
	v_mov_b32_dpp v44, v0 row_ror:2 row_mask:0xf bank_mask:0xf
	v_cmp_gt_f32_e64 s[30:31], v43, v42
	v_cmp_eq_f32_e64 s[0:1], v43, v42
	v_cmp_lt_i32_e64 s[18:19], v44, v0
	s_and_b64 s[0:1], s[0:1], s[18:19]
	s_or_b64 s[30:31], s[30:31], s[0:1]
	v_cndmask_b32_e64 v42, v42, v43, s[30:31]
	v_cndmask_b32_e64 v0, v0, v44, s[30:31]
	ds_bpermute_b32 v43, v12, v42
	s_waitcnt lgkmcnt(1)
	ds_bpermute_b32 v44, v12, v0
	s_waitcnt lgkmcnt(1)
	v_cmp_lt_f32_e64 s[30:31], v42, v43
	v_cmp_nlt_f32_e64 s[0:1], v42, v43
	s_and_saveexec_b64 s[34:35], s[0:1]
	s_cbranch_execz .LBB0_1194
	v_cmp_eq_f32_e64 s[0:1], v42, v43
	s_waitcnt lgkmcnt(0)
	v_cmp_lt_i32_e64 s[18:19], v44, v0
	s_and_b64 s[0:1], s[0:1], s[18:19]
	s_andn2_b64 s[18:19], s[30:31], exec
	s_and_b64 s[0:1], s[0:1], exec
	s_or_b64 s[30:31], s[18:19], s[0:1]
	s_or_b64 exec, exec, s[34:35]
	s_and_saveexec_b64 s[0:1], s[30:31]
	s_cbranch_execnz .LBB0_1195

.LBB0_1200:
	s_or_b64 exec, exec, s[18:19]
	v_cndmask_b32_e64 v25, v38, v1, s[8:9]
	v_cndmask_b32_e64 v24, v38, v5, s[10:11]
	v_cmp_gt_f32_e64 s[0:1], v24, v25
	v_cndmask_b32_e64 v9, v38, v9, s[12:13]
	v_cndmask_b32_e64 v5, v38, v13, s[14:15]
	v_cndmask_b32_e64 v1, v25, v24, s[0:1]
	v_cndmask_b32_e64 v0, v21, v27, s[0:1]
	v_cmp_gt_f32_e64 s[0:1], v9, v1
	s_nop 1
	v_cndmask_b32_e64 v1, v1, v9, s[0:1]
	v_cndmask_b32_e64 v0, v0, v28, s[0:1]
	v_cmp_gt_f32_e64 s[0:1], v5, v1
	s_nop 1
	v_cndmask_b32_e64 v13, v1, v5, s[0:1]
	v_cndmask_b32_e64 v42, v0, v29, s[0:1]
	s_nop 4
	v_mov_b32_dpp v0, v13 row_ror:8 row_mask:0xf bank_mask:0xf
	v_mov_b32_dpp v1, v42 row_ror:8 row_mask:0xf bank_mask:0xf
	v_cmp_gt_f32_e64 s[30:31], v0, v13
	v_cmp_eq_f32_e64 s[0:1], v0, v13
	v_cmp_lt_i32_e64 s[18:19], v1, v42
	s_and_b64 s[0:1], s[0:1], s[18:19]
	s_or_b64 s[30:31], s[30:31], s[0:1]
	v_cndmask_b32_e64 v13, v13, v0, s[30:31]
	v_cndmask_b32_e64 v42, v42, v1, s[30:31]
	s_nop 4
	v_mov_b32_dpp v0, v13 row_ror:4 row_mask:0xf bank_mask:0xf
	v_mov_b32_dpp v1, v42 row_ror:4 row_mask:0xf bank_mask:0xf
	v_cmp_gt_f32_e64 s[30:31], v0, v13
	v_cmp_eq_f32_e64 s[0:1], v0, v13
	v_cmp_lt_i32_e64 s[18:19], v1, v42
	s_and_b64 s[0:1], s[0:1], s[18:19]
	s_or_b64 s[30:31], s[30:31], s[0:1]
	v_cndmask_b32_e64 v13, v13, v0, s[30:31]
	v_cndmask_b32_e64 v42, v42, v1, s[30:31]
	s_nop 4
	v_mov_b32_dpp v0, v13 row_ror:2 row_mask:0xf bank_mask:0xf
	v_mov_b32_dpp v1, v42 row_ror:2 row_mask:0xf bank_mask:0xf
	v_cmp_gt_f32_e64 s[30:31], v0, v13
	v_cmp_eq_f32_e64 s[0:1], v0, v13
	v_cmp_lt_i32_e64 s[18:19], v1, v42
	s_and_b64 s[0:1], s[0:1], s[18:19]
	s_or_b64 s[30:31], s[30:31], s[0:1]
	v_cndmask_b32_e64 v13, v13, v0, s[30:31]
	v_cndmask_b32_e64 v42, v42, v1, s[30:31]
	s_nop 4
	v_mov_b32_dpp v0, v13 row_ror:1 row_mask:0xf bank_mask:0xf
	v_mov_b32_dpp v1, v42 row_ror:1 row_mask:0xf bank_mask:0xf
	v_cmp_gt_f32_e64 s[30:31], v0, v13
	v_cmp_eq_f32_e64 s[0:1], v0, v13
	v_cmp_lt_i32_e64 s[18:19], v1, v42
	s_and_b64 s[0:1], s[0:1], s[18:19]
	s_or_b64 s[30:31], s[30:31], s[0:1]
	v_cndmask_b32_e64 v13, v13, v0, s[30:31]
	v_cndmask_b32_e64 v42, v42, v1, s[30:31]
	v_or_b32_e32 v0, 1, v22
	s_waitcnt lgkmcnt(0)
	v_ashrrev_i32_e32 v1, 31, v0
	v_lshl_add_u64 v[0:1], s[28:29], 0, v[0:1]
	v_lshlrev_b64 v[0:1], 5, v[0:1]
	v_or_b32_e32 v0, s27, v0
	s_and_saveexec_b64 s[18:19], s[6:7]
	s_cbranch_execz .LBB0_1221
	v_cmp_nlt_f32_e64 s[0:1], s42, v13
	v_add_u32_e32 v13, 0x12e0c, v23
	s_and_saveexec_b64 s[30:31], s[0:1]
	s_xor_b64 s[0:1], exec, s[30:31]
	s_cbranch_execz .LBB0_1219
	v_lshlrev_b64 v[44:45], 2, v[0:1]
	v_or_b32_e32 v44, 4, v44
	v_lshl_add_u64 v[46:47], s[2:3], 0, v[44:45]
	v_lshl_add_u64 v[44:45], s[20:21], 0, v[44:45]
	ds_write_b32 v13, v35
	global_store_dword v[46:47], v30, off
	global_store_dword v[44:45], v19, off

.LBB0_1221:
	s_or_b64 exec, exec, s[18:19]
	v_cmp_ne_u32_e64 s[0:1], v21, v42
	s_nop 1
	v_cndmask_b32_e64 v13, v38, v25, s[0:1]
	v_cmp_ne_u32_e64 s[0:1], v27, v42
	s_nop 1
	v_cndmask_b32_e64 v24, v38, v24, s[0:1]
	v_cmp_ne_u32_e64 s[0:1], v28, v42
	s_nop 1
	v_cndmask_b32_e64 v9, v38, v9, s[0:1]
	v_cmp_ne_u32_e64 s[0:1], v29, v42
	s_nop 1
	v_cndmask_b32_e64 v5, v38, v5, s[0:1]
	v_cmp_gt_f32_e64 s[0:1], v24, v13
	s_nop 1
	v_cndmask_b32_e64 v42, v13, v24, s[0:1]
	v_cndmask_b32_e64 v25, v21, v27, s[0:1]
	v_cmp_gt_f32_e64 s[0:1], v9, v42
	s_nop 1
	v_cndmask_b32_e64 v42, v42, v9, s[0:1]
	v_cndmask_b32_e64 v25, v25, v28, s[0:1]
	v_cmp_gt_f32_e64 s[0:1], v5, v42
	s_nop 1
	v_cndmask_b32_e64 v42, v42, v5, s[0:1]
	v_cndmask_b32_e64 v25, v25, v29, s[0:1]
	s_nop 4
	v_mov_b32_dpp v43, v42 row_ror:8 row_mask:0xf bank_mask:0xf
	v_mov_b32_dpp v44, v25 row_ror:8 row_mask:0xf bank_mask:0xf
	v_cmp_gt_f32_e64 s[30:31], v43, v42
	v_cmp_eq_f32_e64 s[0:1], v43, v42
	v_cmp_lt_i32_e64 s[18:19], v44, v25
	s_and_b64 s[0:1], s[0:1], s[18:19]
	s_or_b64 s[30:31], s[30:31], s[0:1]
	v_cndmask_b32_e64 v42, v42, v43, s[30:31]
	v_cndmask_b32_e64 v25, v25, v44, s[30:31]
	s_nop 4
	v_mov_b32_dpp v43, v42 row_ror:4 row_mask:0xf bank_mask:0xf
	v_mov_b32_dpp v44, v25 row_ror:4 row_mask:0xf bank_mask:0xf
	v_cmp_gt_f32_e64 s[30:31], v43, v42
	v_cmp_eq_f32_e64 s[0:1], v43, v42
	v_cmp_lt_i32_e64 s[18:19], v44, v25
	s_and_b64 s[0:1], s[0:1], s[18:19]
	s_or_b64 s[30:31], s[30:31], s[0:1]
	v_cndmask_b32_e64 v42, v42, v43, s[30:31]
	v_cndmask_b32_e64 v25, v25, v44, s[30:31]
	s_nop 4
	v_mov_b32_dpp v43, v42 row_ror:2 row_mask:0xf bank_mask:0xf
	v_mov_b32_dpp v44, v25 row_ror:2 row_mask:0xf bank_mask:0xf
	v_cmp_gt_f32_e64 s[30:31], v43, v42
	v_cmp_eq_f32_e64 s[0:1], v43, v42
	v_cmp_lt_i32_e64 s[18:19], v44, v25
	s_and_b64 s[0:1], s[0:1], s[18:19]
	s_or_b64 s[30:31], s[30:31], s[0:1]
	v_cndmask_b32_e64 v42, v42, v43, s[30:31]
	v_cndmask_b32_e64 v25, v25, v44, s[30:31]
	ds_bpermute_b32 v43, v12, v42
	s_waitcnt lgkmcnt(1)
	ds_bpermute_b32 v44, v12, v25
	s_waitcnt lgkmcnt(1)
	v_cmp_lt_f32_e64 s[30:31], v42, v43
	v_cmp_nlt_f32_e64 s[0:1], v42, v43
	s_and_saveexec_b64 s[34:35], s[0:1]
	s_cbranch_execz .LBB0_1236
	v_cmp_eq_f32_e64 s[0:1], v42, v43
	s_waitcnt lgkmcnt(0)
	v_cmp_lt_i32_e64 s[18:19], v44, v25
	s_and_b64 s[0:1], s[0:1], s[18:19]
	s_andn2_b64 s[18:19], s[30:31], exec
	s_and_b64 s[0:1], s[0:1], exec
	s_or_b64 s[30:31], s[18:19], s[0:1]
	s_or_b64 exec, exec, s[34:35]
	s_and_saveexec_b64 s[0:1], s[30:31]
	s_cbranch_execnz .LBB0_1237

.LBB0_1242:
	s_or_b64 exec, exec, s[18:19]
	v_cmp_ne_u32_e64 s[0:1], v21, v25
	s_nop 1
	v_cndmask_b32_e64 v13, v38, v13, s[0:1]
	v_cmp_ne_u32_e64 s[0:1], v27, v25
	s_nop 1
	v_cndmask_b32_e64 v24, v38, v24, s[0:1]
	v_cmp_ne_u32_e64 s[0:1], v28, v25
	s_nop 1
	v_cndmask_b32_e64 v9, v38, v9, s[0:1]
	v_cmp_ne_u32_e64 s[0:1], v29, v25
	s_nop 1
	v_cndmask_b32_e64 v25, v38, v5, s[0:1]
	v_cmp_gt_f32_e64 s[0:1], v24, v13
	s_nop 1
	v_cndmask_b32_e64 v13, v13, v24, s[0:1]
	v_cndmask_b32_e64 v5, v21, v27, s[0:1]
	v_cmp_gt_f32_e64 s[0:1], v9, v13
	s_nop 1
	v_cndmask_b32_e64 v9, v13, v9, s[0:1]
	v_cndmask_b32_e64 v5, v5, v28, s[0:1]
	v_cmp_gt_f32_e64 s[0:1], v25, v9
	s_nop 1
	v_cndmask_b32_e64 v9, v9, v25, s[0:1]
	v_cndmask_b32_e64 v5, v5, v29, s[0:1]
	s_nop 4
	v_mov_b32_dpp v13, v9 row_ror:8 row_mask:0xf bank_mask:0xf
	v_mov_b32_dpp v24, v5 row_ror:8 row_mask:0xf bank_mask:0xf
	v_cmp_gt_f32_e64 s[30:31], v13, v9
	v_cmp_eq_f32_e64 s[0:1], v13, v9
	v_cmp_lt_i32_e64 s[18:19], v24, v5
	s_and_b64 s[0:1], s[0:1], s[18:19]
	s_or_b64 s[30:31], s[30:31], s[0:1]
	v_cndmask_b32_e64 v9, v9, v13, s[30:31]
	v_cndmask_b32_e64 v5, v5, v24, s[30:31]
	s_nop 4
	v_mov_b32_dpp v13, v9 row_ror:4 row_mask:0xf bank_mask:0xf
	v_mov_b32_dpp v24, v5 row_ror:4 row_mask:0xf bank_mask:0xf
	v_cmp_gt_f32_e64 s[30:31], v13, v9
	v_cmp_eq_f32_e64 s[0:1], v13, v9
	v_cmp_lt_i32_e64 s[18:19], v24, v5
	s_and_b64 s[0:1], s[0:1], s[18:19]
	s_or_b64 s[30:31], s[30:31], s[0:1]
	v_cndmask_b32_e64 v9, v9, v13, s[30:31]
	v_cndmask_b32_e64 v5, v5, v24, s[30:31]
	s_nop 4
	v_mov_b32_dpp v13, v9 row_ror:2 row_mask:0xf bank_mask:0xf
	v_mov_b32_dpp v24, v5 row_ror:2 row_mask:0xf bank_mask:0xf
	v_cmp_gt_f32_e64 s[30:31], v13, v9
	v_cmp_eq_f32_e64 s[0:1], v13, v9
	v_cmp_lt_i32_e64 s[18:19], v24, v5
	s_and_b64 s[0:1], s[0:1], s[18:19]
	s_or_b64 s[30:31], s[30:31], s[0:1]
	v_cndmask_b32_e64 v9, v9, v13, s[30:31]
	v_cndmask_b32_e64 v5, v5, v24, s[30:31]
	ds_bpermute_b32 v13, v12, v9
	s_waitcnt lgkmcnt(1)
	ds_bpermute_b32 v24, v12, v5
	s_waitcnt lgkmcnt(1)
	v_cmp_lt_f32_e64 s[30:31], v9, v13
	v_cmp_nlt_f32_e64 s[0:1], v9, v13
	s_and_saveexec_b64 s[34:35], s[0:1]
	s_cbranch_execz .LBB0_1257
	v_cmp_eq_f32_e64 s[0:1], v9, v13
	s_waitcnt lgkmcnt(0)
	v_cmp_lt_i32_e64 s[18:19], v24, v5
	s_and_b64 s[0:1], s[0:1], s[18:19]
	s_andn2_b64 s[18:19], s[30:31], exec
	s_and_b64 s[0:1], s[0:1], exec
	s_or_b64 s[30:31], s[18:19], s[0:1]
	s_or_b64 exec, exec, s[34:35]
	s_and_saveexec_b64 s[0:1], s[30:31]
	s_cbranch_execnz .LBB0_1258

.LBB0_1263:
	s_or_b64 exec, exec, s[18:19]
	v_cndmask_b32_e64 v9, v38, v2, s[8:9]
	v_cndmask_b32_e64 v6, v38, v6, s[10:11]
	v_cmp_gt_f32_e64 s[0:1], v6, v9
	v_cndmask_b32_e64 v5, v38, v10, s[12:13]
	v_cndmask_b32_e64 v2, v38, v14, s[14:15]
	v_cndmask_b32_e64 v1, v9, v6, s[0:1]
	v_cndmask_b32_e64 v0, v21, v27, s[0:1]
	v_cmp_gt_f32_e64 s[0:1], v5, v1
	s_nop 1
	v_cndmask_b32_e64 v1, v1, v5, s[0:1]
	v_cndmask_b32_e64 v0, v0, v28, s[0:1]
	v_cmp_gt_f32_e64 s[0:1], v2, v1
	s_nop 1
	v_cndmask_b32_e64 v13, v1, v2, s[0:1]
	v_cndmask_b32_e64 v10, v0, v29, s[0:1]
	s_nop 4
	v_mov_b32_dpp v0, v13 row_ror:8 row_mask:0xf bank_mask:0xf
	v_mov_b32_dpp v1, v10 row_ror:8 row_mask:0xf bank_mask:0xf
	v_cmp_gt_f32_e64 s[30:31], v0, v13
	v_cmp_eq_f32_e64 s[0:1], v0, v13
	v_cmp_lt_i32_e64 s[18:19], v1, v10
	s_and_b64 s[0:1], s[0:1], s[18:19]
	s_or_b64 s[30:31], s[30:31], s[0:1]
	v_cndmask_b32_e64 v13, v13, v0, s[30:31]
	v_cndmask_b32_e64 v10, v10, v1, s[30:31]
	s_nop 4
	v_mov_b32_dpp v0, v13 row_ror:4 row_mask:0xf bank_mask:0xf
	v_mov_b32_dpp v1, v10 row_ror:4 row_mask:0xf bank_mask:0xf
	v_cmp_gt_f32_e64 s[30:31], v0, v13
	v_cmp_eq_f32_e64 s[0:1], v0, v13
	v_cmp_lt_i32_e64 s[18:19], v1, v10
	s_and_b64 s[0:1], s[0:1], s[18:19]
	s_or_b64 s[30:31], s[30:31], s[0:1]
	v_cndmask_b32_e64 v13, v13, v0, s[30:31]
	v_cndmask_b32_e64 v10, v10, v1, s[30:31]
	s_nop 4
	v_mov_b32_dpp v0, v13 row_ror:2 row_mask:0xf bank_mask:0xf
	v_mov_b32_dpp v1, v10 row_ror:2 row_mask:0xf bank_mask:0xf
	v_cmp_gt_f32_e64 s[30:31], v0, v13
	v_cmp_eq_f32_e64 s[0:1], v0, v13
	v_cmp_lt_i32_e64 s[18:19], v1, v10
	s_and_b64 s[0:1], s[0:1], s[18:19]
	s_or_b64 s[30:31], s[30:31], s[0:1]
	v_cndmask_b32_e64 v13, v13, v0, s[30:31]
	v_cndmask_b32_e64 v10, v10, v1, s[30:31]
	s_nop 4
	v_mov_b32_dpp v0, v13 row_ror:1 row_mask:0xf bank_mask:0xf
	v_mov_b32_dpp v1, v10 row_ror:1 row_mask:0xf bank_mask:0xf
	v_cmp_gt_f32_e64 s[30:31], v0, v13
	v_cmp_eq_f32_e64 s[0:1], v0, v13
	v_cmp_lt_i32_e64 s[18:19], v1, v10
	s_and_b64 s[0:1], s[0:1], s[18:19]
	s_or_b64 s[30:31], s[30:31], s[0:1]
	v_cndmask_b32_e64 v13, v13, v0, s[30:31]
	v_cndmask_b32_e64 v10, v10, v1, s[30:31]
	v_or_b32_e32 v0, 2, v22
	s_waitcnt lgkmcnt(0)
	v_ashrrev_i32_e32 v1, 31, v0
	v_lshl_add_u64 v[0:1], s[28:29], 0, v[0:1]
	v_lshlrev_b64 v[0:1], 5, v[0:1]
	v_or_b32_e32 v0, s27, v0
	s_and_saveexec_b64 s[18:19], s[6:7]
	s_cbranch_execz .LBB0_1284
	v_cmp_nlt_f32_e64 s[0:1], s42, v13
	v_add_u32_e32 v13, 0x12e18, v23
	s_and_saveexec_b64 s[30:31], s[0:1]
	s_xor_b64 s[0:1], exec, s[30:31]
	s_cbranch_execz .LBB0_1282
	v_lshlrev_b64 v[24:25], 2, v[0:1]
	v_or_b32_e32 v24, 4, v24
	v_lshl_add_u64 v[42:43], s[2:3], 0, v[24:25]
	v_lshl_add_u64 v[24:25], s[20:21], 0, v[24:25]
	ds_write_b32 v13, v35
	global_store_dword v[42:43], v30, off
	global_store_dword v[24:25], v19, off

.LBB0_1284:
	s_or_b64 exec, exec, s[18:19]
	v_cmp_ne_u32_e64 s[0:1], v21, v10
	s_nop 1
	v_cndmask_b32_e64 v9, v38, v9, s[0:1]
	v_cmp_ne_u32_e64 s[0:1], v27, v10
	s_nop 1
	v_cndmask_b32_e64 v6, v38, v6, s[0:1]
	v_cmp_ne_u32_e64 s[0:1], v28, v10
	s_nop 1
	v_cndmask_b32_e64 v5, v38, v5, s[0:1]
	v_cmp_ne_u32_e64 s[0:1], v29, v10
	s_nop 1
	v_cndmask_b32_e64 v2, v38, v2, s[0:1]
	v_cmp_gt_f32_e64 s[0:1], v6, v9
	s_nop 1
	v_cndmask_b32_e64 v13, v9, v6, s[0:1]
	v_cndmask_b32_e64 v10, v21, v27, s[0:1]
	v_cmp_gt_f32_e64 s[0:1], v5, v13
	s_nop 1
	v_cndmask_b32_e64 v13, v13, v5, s[0:1]
	v_cndmask_b32_e64 v10, v10, v28, s[0:1]
	v_cmp_gt_f32_e64 s[0:1], v2, v13
	s_nop 1
	v_cndmask_b32_e64 v13, v13, v2, s[0:1]
	v_cndmask_b32_e64 v10, v10, v29, s[0:1]
	s_nop 4
	v_mov_b32_dpp v14, v13 row_ror:8 row_mask:0xf bank_mask:0xf
	v_mov_b32_dpp v24, v10 row_ror:8 row_mask:0xf bank_mask:0xf
	v_cmp_gt_f32_e64 s[30:31], v14, v13
	v_cmp_eq_f32_e64 s[0:1], v14, v13
	v_cmp_lt_i32_e64 s[18:19], v24, v10
	s_and_b64 s[0:1], s[0:1], s[18:19]
	s_or_b64 s[30:31], s[30:31], s[0:1]
	v_cndmask_b32_e64 v13, v13, v14, s[30:31]
	v_cndmask_b32_e64 v10, v10, v24, s[30:31]
	s_nop 4
	v_mov_b32_dpp v14, v13 row_ror:4 row_mask:0xf bank_mask:0xf
	v_mov_b32_dpp v24, v10 row_ror:4 row_mask:0xf bank_mask:0xf
	v_cmp_gt_f32_e64 s[30:31], v14, v13
	v_cmp_eq_f32_e64 s[0:1], v14, v13
	v_cmp_lt_i32_e64 s[18:19], v24, v10
	s_and_b64 s[0:1], s[0:1], s[18:19]
	s_or_b64 s[30:31], s[30:31], s[0:1]
	v_cndmask_b32_e64 v13, v13, v14, s[30:31]
	v_cndmask_b32_e64 v10, v10, v24, s[30:31]
	s_nop 4
	v_mov_b32_dpp v14, v13 row_ror:2 row_mask:0xf bank_mask:0xf
	v_mov_b32_dpp v24, v10 row_ror:2 row_mask:0xf bank_mask:0xf
	v_cmp_gt_f32_e64 s[30:31], v14, v13
	v_cmp_eq_f32_e64 s[0:1], v14, v13
	v_cmp_lt_i32_e64 s[18:19], v24, v10
	s_and_b64 s[0:1], s[0:1], s[18:19]
	s_or_b64 s[30:31], s[30:31], s[0:1]
	v_cndmask_b32_e64 v13, v13, v14, s[30:31]
	v_cndmask_b32_e64 v10, v10, v24, s[30:31]
	ds_bpermute_b32 v14, v12, v13
	s_waitcnt lgkmcnt(1)
	ds_bpermute_b32 v24, v12, v10
	s_waitcnt lgkmcnt(1)
	v_cmp_lt_f32_e64 s[30:31], v13, v14
	v_cmp_nlt_f32_e64 s[0:1], v13, v14
	s_and_saveexec_b64 s[34:35], s[0:1]
	s_cbranch_execz .LBB0_1299
	v_cmp_eq_f32_e64 s[0:1], v13, v14
	s_waitcnt lgkmcnt(0)
	v_cmp_lt_i32_e64 s[18:19], v24, v10
	s_and_b64 s[0:1], s[0:1], s[18:19]
	s_andn2_b64 s[18:19], s[30:31], exec
	s_and_b64 s[0:1], s[0:1], exec
	s_or_b64 s[30:31], s[18:19], s[0:1]
	s_or_b64 exec, exec, s[34:35]
	s_and_saveexec_b64 s[0:1], s[30:31]
	s_cbranch_execnz .LBB0_1300

.LBB0_1305:
	s_or_b64 exec, exec, s[18:19]
	v_cmp_ne_u32_e64 s[0:1], v21, v10
	s_nop 1
	v_cndmask_b32_e64 v9, v38, v9, s[0:1]
	v_cmp_ne_u32_e64 s[0:1], v27, v10
	s_nop 1
	v_cndmask_b32_e64 v6, v38, v6, s[0:1]
	v_cmp_ne_u32_e64 s[0:1], v28, v10
	s_nop 1
	v_cndmask_b32_e64 v5, v38, v5, s[0:1]
	v_cmp_ne_u32_e64 s[0:1], v29, v10
	s_nop 1
	v_cndmask_b32_e64 v10, v38, v2, s[0:1]
	v_cmp_gt_f32_e64 s[0:1], v6, v9
	s_nop 1
	v_cndmask_b32_e64 v6, v9, v6, s[0:1]
	v_cndmask_b32_e64 v2, v21, v27, s[0:1]
	v_cmp_gt_f32_e64 s[0:1], v5, v6
	s_nop 1
	v_cndmask_b32_e64 v5, v6, v5, s[0:1]
	v_cndmask_b32_e64 v2, v2, v28, s[0:1]
	v_cmp_gt_f32_e64 s[0:1], v10, v5
	s_nop 1
	v_cndmask_b32_e64 v5, v5, v10, s[0:1]
	v_cndmask_b32_e64 v2, v2, v29, s[0:1]
	s_nop 4
	v_mov_b32_dpp v6, v5 row_ror:8 row_mask:0xf bank_mask:0xf
	v_mov_b32_dpp v9, v2 row_ror:8 row_mask:0xf bank_mask:0xf
	v_cmp_gt_f32_e64 s[30:31], v6, v5
	v_cmp_eq_f32_e64 s[0:1], v6, v5
	v_cmp_lt_i32_e64 s[18:19], v9, v2
	s_and_b64 s[0:1], s[0:1], s[18:19]
	s_or_b64 s[30:31], s[30:31], s[0:1]
	v_cndmask_b32_e64 v5, v5, v6, s[30:31]
	v_cndmask_b32_e64 v2, v2, v9, s[30:31]
	s_nop 4
	v_mov_b32_dpp v6, v5 row_ror:4 row_mask:0xf bank_mask:0xf
	v_mov_b32_dpp v9, v2 row_ror:4 row_mask:0xf bank_mask:0xf
	v_cmp_gt_f32_e64 s[30:31], v6, v5
	v_cmp_eq_f32_e64 s[0:1], v6, v5
	v_cmp_lt_i32_e64 s[18:19], v9, v2
	s_and_b64 s[0:1], s[0:1], s[18:19]
	s_or_b64 s[30:31], s[30:31], s[0:1]
	v_cndmask_b32_e64 v5, v5, v6, s[30:31]
	v_cndmask_b32_e64 v2, v2, v9, s[30:31]
	s_nop 4
	v_mov_b32_dpp v6, v5 row_ror:2 row_mask:0xf bank_mask:0xf
	v_mov_b32_dpp v9, v2 row_ror:2 row_mask:0xf bank_mask:0xf
	v_cmp_gt_f32_e64 s[30:31], v6, v5
	v_cmp_eq_f32_e64 s[0:1], v6, v5
	v_cmp_lt_i32_e64 s[18:19], v9, v2
	s_and_b64 s[0:1], s[0:1], s[18:19]
	s_or_b64 s[30:31], s[30:31], s[0:1]
	v_cndmask_b32_e64 v5, v5, v6, s[30:31]
	v_cndmask_b32_e64 v2, v2, v9, s[30:31]
	ds_bpermute_b32 v6, v12, v5
	s_waitcnt lgkmcnt(1)
	ds_bpermute_b32 v9, v12, v2
	s_waitcnt lgkmcnt(1)
	v_cmp_lt_f32_e64 s[30:31], v5, v6
	v_cmp_nlt_f32_e64 s[0:1], v5, v6
	s_and_saveexec_b64 s[34:35], s[0:1]
	s_cbranch_execz .LBB0_1320
	v_cmp_eq_f32_e64 s[0:1], v5, v6
	s_waitcnt lgkmcnt(0)
	v_cmp_lt_i32_e64 s[18:19], v9, v2
	s_and_b64 s[0:1], s[0:1], s[18:19]
	s_andn2_b64 s[18:19], s[30:31], exec
	s_and_b64 s[0:1], s[0:1], exec
	s_or_b64 s[30:31], s[18:19], s[0:1]
	s_or_b64 exec, exec, s[34:35]
	s_and_saveexec_b64 s[0:1], s[30:31]
	s_cbranch_execnz .LBB0_1321

.LBB0_1326:
	s_or_b64 exec, exec, s[18:19]
	v_cndmask_b32_e64 v6, v38, v3, s[8:9]
	v_cndmask_b32_e64 v5, v38, v7, s[10:11]
	v_cmp_gt_f32_e64 s[0:1], v5, v6
	v_cndmask_b32_e64 v3, v38, v11, s[12:13]
	v_cndmask_b32_e64 v2, v38, v15, s[14:15]
	v_cndmask_b32_e64 v1, v6, v5, s[0:1]
	v_cndmask_b32_e64 v0, v21, v27, s[0:1]
	v_cmp_gt_f32_e64 s[0:1], v3, v1
	s_nop 1
	v_cndmask_b32_e64 v1, v1, v3, s[0:1]
	v_cndmask_b32_e64 v0, v0, v28, s[0:1]
	v_cmp_gt_f32_e64 s[0:1], v2, v1
	s_waitcnt lgkmcnt(0)
	s_nop 0
	v_cndmask_b32_e64 v9, v1, v2, s[0:1]
	v_cndmask_b32_e64 v7, v0, v29, s[0:1]
	s_nop 4
	v_mov_b32_dpp v0, v9 row_ror:8 row_mask:0xf bank_mask:0xf
	v_mov_b32_dpp v1, v7 row_ror:8 row_mask:0xf bank_mask:0xf
	v_cmp_gt_f32_e64 s[10:11], v0, v9
	v_cmp_eq_f32_e64 s[0:1], v0, v9
	v_cmp_lt_i32_e64 s[8:9], v1, v7
	s_and_b64 s[0:1], s[0:1], s[8:9]
	s_or_b64 s[10:11], s[10:11], s[0:1]
	v_cndmask_b32_e64 v9, v9, v0, s[10:11]
	v_cndmask_b32_e64 v7, v7, v1, s[10:11]
	s_nop 4
	v_mov_b32_dpp v0, v9 row_ror:4 row_mask:0xf bank_mask:0xf
	v_mov_b32_dpp v1, v7 row_ror:4 row_mask:0xf bank_mask:0xf
	v_cmp_gt_f32_e64 s[10:11], v0, v9
	v_cmp_eq_f32_e64 s[0:1], v0, v9
	v_cmp_lt_i32_e64 s[8:9], v1, v7
	s_and_b64 s[0:1], s[0:1], s[8:9]
	s_or_b64 s[10:11], s[10:11], s[0:1]
	v_cndmask_b32_e64 v9, v9, v0, s[10:11]
	v_cndmask_b32_e64 v7, v7, v1, s[10:11]
	s_nop 4
	v_mov_b32_dpp v0, v9 row_ror:2 row_mask:0xf bank_mask:0xf
	v_mov_b32_dpp v1, v7 row_ror:2 row_mask:0xf bank_mask:0xf
	v_cmp_gt_f32_e64 s[10:11], v0, v9
	v_cmp_eq_f32_e64 s[0:1], v0, v9
	v_cmp_lt_i32_e64 s[8:9], v1, v7
	s_and_b64 s[0:1], s[0:1], s[8:9]
	s_or_b64 s[10:11], s[10:11], s[0:1]
	v_cndmask_b32_e64 v9, v9, v0, s[10:11]
	v_cndmask_b32_e64 v7, v7, v1, s[10:11]
	s_nop 4
	v_mov_b32_dpp v0, v9 row_ror:1 row_mask:0xf bank_mask:0xf
	v_mov_b32_dpp v1, v7 row_ror:1 row_mask:0xf bank_mask:0xf
	v_cmp_gt_f32_e64 s[10:11], v0, v9
	v_cmp_eq_f32_e64 s[0:1], v0, v9
	v_cmp_lt_i32_e64 s[8:9], v1, v7
	s_and_b64 s[0:1], s[0:1], s[8:9]
	s_or_b64 s[10:11], s[10:11], s[0:1]
	v_cndmask_b32_e64 v9, v9, v0, s[10:11]
	v_cndmask_b32_e64 v7, v7, v1, s[10:11]
	v_or_b32_e32 v0, 3, v22
	s_waitcnt lgkmcnt(0)
	v_ashrrev_i32_e32 v1, 31, v0
	v_lshl_add_u64 v[0:1], s[28:29], 0, v[0:1]
	v_lshlrev_b64 v[0:1], 5, v[0:1]
	v_or_b32_e32 v0, s27, v0
	s_and_saveexec_b64 s[8:9], s[6:7]
	s_cbranch_execz .LBB0_1347
	v_cmp_nlt_f32_e64 s[0:1], s42, v9
	v_add_u32_e32 v9, 0x12e24, v23
	s_and_saveexec_b64 s[10:11], s[0:1]
	s_xor_b64 s[0:1], exec, s[10:11]
	s_cbranch_execz .LBB0_1345
	v_lshlrev_b64 v[10:11], 2, v[0:1]
	v_or_b32_e32 v10, 4, v10
	v_lshl_add_u64 v[14:15], s[2:3], 0, v[10:11]
	v_lshl_add_u64 v[10:11], s[20:21], 0, v[10:11]
	ds_write_b32 v9, v35
	global_store_dword v[14:15], v30, off
	global_store_dword v[10:11], v19, off

.LBB0_1347:
	s_or_b64 exec, exec, s[8:9]
	v_cmp_ne_u32_e64 s[0:1], v21, v7
	s_nop 1
	v_cndmask_b32_e64 v6, v38, v6, s[0:1]
	v_cmp_ne_u32_e64 s[0:1], v27, v7
	s_nop 1
	v_cndmask_b32_e64 v5, v38, v5, s[0:1]
	v_cmp_ne_u32_e64 s[0:1], v28, v7
	s_nop 1
	v_cndmask_b32_e64 v3, v38, v3, s[0:1]
	v_cmp_ne_u32_e64 s[0:1], v29, v7
	s_nop 1
	v_cndmask_b32_e64 v2, v38, v2, s[0:1]
	v_cmp_gt_f32_e64 s[0:1], v5, v6
	s_nop 1
	v_cndmask_b32_e64 v9, v6, v5, s[0:1]
	v_cndmask_b32_e64 v7, v21, v27, s[0:1]
	v_cmp_gt_f32_e64 s[0:1], v3, v9
	s_nop 1
	v_cndmask_b32_e64 v9, v9, v3, s[0:1]
	v_cndmask_b32_e64 v7, v7, v28, s[0:1]
	v_cmp_gt_f32_e64 s[0:1], v2, v9
	s_nop 1
	v_cndmask_b32_e64 v9, v9, v2, s[0:1]
	v_cndmask_b32_e64 v7, v7, v29, s[0:1]
	s_nop 4
	v_mov_b32_dpp v10, v9 row_ror:8 row_mask:0xf bank_mask:0xf
	v_mov_b32_dpp v11, v7 row_ror:8 row_mask:0xf bank_mask:0xf
	v_cmp_gt_f32_e64 s[10:11], v10, v9
	v_cmp_eq_f32_e64 s[0:1], v10, v9
	v_cmp_lt_i32_e64 s[8:9], v11, v7
	s_and_b64 s[0:1], s[0:1], s[8:9]
	s_or_b64 s[10:11], s[10:11], s[0:1]
	v_cndmask_b32_e64 v9, v9, v10, s[10:11]
	v_cndmask_b32_e64 v7, v7, v11, s[10:11]
	s_nop 4
	v_mov_b32_dpp v10, v9 row_ror:4 row_mask:0xf bank_mask:0xf
	v_mov_b32_dpp v11, v7 row_ror:4 row_mask:0xf bank_mask:0xf
	v_cmp_gt_f32_e64 s[10:11], v10, v9
	v_cmp_eq_f32_e64 s[0:1], v10, v9
	v_cmp_lt_i32_e64 s[8:9], v11, v7
	s_and_b64 s[0:1], s[0:1], s[8:9]
	s_or_b64 s[10:11], s[10:11], s[0:1]
	v_cndmask_b32_e64 v9, v9, v10, s[10:11]
	v_cndmask_b32_e64 v7, v7, v11, s[10:11]
	s_nop 4
	v_mov_b32_dpp v10, v9 row_ror:2 row_mask:0xf bank_mask:0xf
	v_mov_b32_dpp v11, v7 row_ror:2 row_mask:0xf bank_mask:0xf
	v_cmp_gt_f32_e64 s[10:11], v10, v9
	v_cmp_eq_f32_e64 s[0:1], v10, v9
	v_cmp_lt_i32_e64 s[8:9], v11, v7
	s_and_b64 s[0:1], s[0:1], s[8:9]
	s_or_b64 s[10:11], s[10:11], s[0:1]
	v_cndmask_b32_e64 v9, v9, v10, s[10:11]
	v_cndmask_b32_e64 v7, v7, v11, s[10:11]
	ds_bpermute_b32 v10, v12, v9
	s_waitcnt lgkmcnt(1)
	ds_bpermute_b32 v11, v12, v7
	s_waitcnt lgkmcnt(1)
	v_cmp_lt_f32_e64 s[10:11], v9, v10
	v_cmp_nlt_f32_e64 s[0:1], v9, v10
	s_and_saveexec_b64 s[12:13], s[0:1]
	s_cbranch_execz .LBB0_1362
	v_cmp_eq_f32_e64 s[0:1], v9, v10
	s_waitcnt lgkmcnt(0)
	v_cmp_lt_i32_e64 s[8:9], v11, v7
	s_and_b64 s[0:1], s[0:1], s[8:9]
	s_andn2_b64 s[8:9], s[10:11], exec
	s_and_b64 s[0:1], s[0:1], exec
	s_or_b64 s[10:11], s[8:9], s[0:1]
	s_or_b64 exec, exec, s[12:13]
	s_and_saveexec_b64 s[0:1], s[10:11]
	s_cbranch_execnz .LBB0_1363

.LBB0_1368:
	s_or_b64 exec, exec, s[8:9]
	v_cmp_ne_u32_e64 s[0:1], v21, v7
	s_nop 1
	v_cndmask_b32_e64 v6, v38, v6, s[0:1]
	v_cmp_ne_u32_e64 s[0:1], v27, v7
	s_nop 1
	v_cndmask_b32_e64 v5, v38, v5, s[0:1]
	v_cmp_ne_u32_e64 s[0:1], v28, v7
	s_nop 1
	v_cndmask_b32_e64 v3, v38, v3, s[0:1]
	v_cmp_ne_u32_e64 s[0:1], v29, v7
	s_nop 1
	v_cndmask_b32_e64 v7, v38, v2, s[0:1]
	v_cmp_gt_f32_e64 s[0:1], v5, v6
	s_nop 1
	v_cndmask_b32_e64 v5, v6, v5, s[0:1]
	v_cndmask_b32_e64 v2, v21, v27, s[0:1]
	v_cmp_gt_f32_e64 s[0:1], v3, v5
	s_nop 1
	v_cndmask_b32_e64 v3, v5, v3, s[0:1]
	v_cndmask_b32_e64 v2, v2, v28, s[0:1]
	v_cmp_gt_f32_e64 s[0:1], v7, v3
	s_nop 1
	v_cndmask_b32_e64 v3, v3, v7, s[0:1]
	v_cndmask_b32_e64 v2, v2, v29, s[0:1]
	s_nop 4
	v_mov_b32_dpp v5, v3 row_ror:8 row_mask:0xf bank_mask:0xf
	v_mov_b32_dpp v6, v2 row_ror:8 row_mask:0xf bank_mask:0xf
	v_cmp_gt_f32_e64 s[10:11], v5, v3
	v_cmp_eq_f32_e64 s[0:1], v5, v3
	v_cmp_lt_i32_e64 s[8:9], v6, v2
	s_and_b64 s[0:1], s[0:1], s[8:9]
	s_or_b64 s[10:11], s[10:11], s[0:1]
	v_cndmask_b32_e64 v3, v3, v5, s[10:11]
	v_cndmask_b32_e64 v2, v2, v6, s[10:11]
	s_nop 4
	v_mov_b32_dpp v5, v3 row_ror:4 row_mask:0xf bank_mask:0xf
	v_mov_b32_dpp v4, v2 row_ror:4 row_mask:0xf bank_mask:0xf
	v_cmp_gt_f32_e64 s[10:11], v5, v3
	v_cmp_eq_f32_e64 s[0:1], v5, v3
	v_cmp_lt_i32_e64 s[8:9], v4, v2
	s_and_b64 s[0:1], s[0:1], s[8:9]
	s_or_b64 s[10:11], s[10:11], s[0:1]
	v_cndmask_b32_e64 v3, v3, v5, s[10:11]
	v_cndmask_b32_e64 v2, v2, v4, s[10:11]
	s_waitcnt lgkmcnt(0)
	s_nop 4
	v_mov_b32_dpp v4, v3 row_ror:2 row_mask:0xf bank_mask:0xf
	v_mov_b32_dpp v5, v2 row_ror:2 row_mask:0xf bank_mask:0xf
	v_cmp_gt_f32_e64 s[10:11], v4, v3
	v_cmp_eq_f32_e64 s[0:1], v4, v3
	v_cmp_lt_i32_e64 s[8:9], v5, v2
	s_and_b64 s[0:1], s[0:1], s[8:9]
	s_or_b64 s[10:11], s[10:11], s[0:1]
	v_cndmask_b32_e64 v3, v3, v4, s[10:11]
	v_cndmask_b32_e64 v2, v2, v5, s[10:11]
	ds_bpermute_b32 v4, v12, v3
	s_waitcnt lgkmcnt(1)
	ds_bpermute_b32 v5, v12, v2
	s_waitcnt lgkmcnt(1)
	v_cmp_lt_f32_e64 s[10:11], v3, v4
	v_cmp_nlt_f32_e64 s[0:1], v3, v4
	s_and_saveexec_b64 s[12:13], s[0:1]
	s_cbranch_execz .LBB0_1383
	v_cmp_eq_f32_e64 s[0:1], v3, v4
	s_waitcnt lgkmcnt(0)
	v_cmp_lt_i32_e64 s[8:9], v5, v2
	s_and_b64 s[0:1], s[0:1], s[8:9]
	s_andn2_b64 s[8:9], s[10:11], exec
	s_and_b64 s[0:1], s[0:1], exec
	s_or_b64 s[10:11], s[8:9], s[0:1]
	s_or_b64 exec, exec, s[12:13]
	s_and_saveexec_b64 s[0:1], s[10:11]
	s_cbranch_execnz .LBB0_1384
